# combo plus: XCD leaders among conversion workgroups do not wait at the first barrier; ada tile stored write-through so its publish needs no L2 write-back
# baseline (speedup 1.0000x reference)
; __device__ __forceinline__ unsigned xb_ld(unsigned* p)              { return __hip_atomic_load(p, __ATOMIC_RELAXED, __HIP_MEMORY_SCOPE_AGENT); }
; __device__ __forceinline__ unsigned xb_add(unsigned* p, unsigned v) { return __hip_atomic_fetch_add(p, v, __ATOMIC_RELAXED, __HIP_MEMORY_SCOPE_AGENT); }
; #define XB_SPIN(cond, bar) do { unsigned _sp = 0; while (cond) { __builtin_amdgcn_s_sleep(1); \
;     if ((++_sp & 255u) == 0u) { if (xb_ld(&(bar)[XB_TMO])) break; if (_sp > XB_SPIN_CAP) { atomicAdd(&(bar)[XB_TMO], 1u); break; } } } } while (0)
; __device__ __forceinline__ void xcd_barrier(const XcdBarrier& b) {
;     ...
;         const unsigned old = xb_add(&bar[XB_XSUB(b.x)], 1u);
;         const unsigned gen = old / nloc;
;         if (old + 1u == (gen + 1u) * nloc) {
;             __builtin_amdgcn_fence(__ATOMIC_RELEASE, "agent");
;             asm volatile("s_waitcnt vmcnt(0)" ::: "memory");
;             const unsigned og = xb_add(&bar[XB_TOP], 1u);
;             const unsigned tg = og / nx;
;             if (og + 1u == (tg + 1u) * nx) xb_add(&bar[XB_TOPGEN], 1u);
;             else XB_SPIN(xb_ld(&bar[XB_TOPGEN]) == tg, bar);
;             __builtin_amdgcn_fence(__ATOMIC_ACQUIRE, "agent");
;             xb_add(&bar[XB_XGEN(b.x)], 1u);
.LBB0_71:
	s_or_b64 exec, exec, s[8:9]
	v_cvt_f32_u32_e32 v3, v0
	s_waitcnt vmcnt(0)
	v_readfirstlane_b32 s0, v2
	s_add_u32 s8, s84, 0xc13500
	s_addc_u32 s9, s85, 0
	v_rcp_iflag_f32_e32 v3, v3
	v_add_u32_e32 v1, s0, v1
	v_add_u32_e32 v4, 1, v1
	s_mov_b64 s[10:11], -1
	v_mul_f32_e32 v2, 0x4f7ffffe, v3
	v_cvt_u32_f32_e32 v2, v2
	v_sub_u32_e32 v3, 0, v0
	v_mul_lo_u32 v3, v3, v2
	v_mul_hi_u32 v3, v2, v3
	v_add_u32_e32 v2, v2, v3
	v_mul_hi_u32 v2, v1, v2
	v_mul_lo_u32 v3, v2, v0
	v_sub_u32_e32 v1, v1, v3
	v_add_u32_e32 v5, 1, v2
	v_cmp_ge_u32_e32 vcc, v1, v0
	v_sub_u32_e32 v3, v1, v0
	s_nop 0
	v_cndmask_b32_e32 v2, v2, v5, vcc
	v_cndmask_b32_e32 v1, v1, v3, vcc
	v_add_u32_e32 v3, 1, v2
	v_cmp_ge_u32_e32 vcc, v1, v0
	s_nop 1
	v_cndmask_b32_e32 v2, v2, v3, vcc
	v_mul_lo_u32 v1, v0, v2
	v_add_u32_e32 v0, v1, v0
	v_cmp_ne_u32_e32 vcc, v4, v0
	v_mov_b64_e32 v[0:1], s[8:9]
	s_and_saveexec_b64 s[0:1], vcc
	s_cbranch_execz .LBB0_83
	s_cmp_gt_u32 s2, 47
	s_cbranch_scc0 .Lb1_lspin
	s_mov_b64 s[14:15], 0
	s_mov_b64 s[12:13], exec
	s_branch .LBB0_82
.Lb1_lspin:
	v_mov_b32_e32 v0, 0
	global_load_dword v1, v0, s[8:9] sc1
	s_mov_b64 s[14:15], 0
	s_waitcnt vmcnt(0)
	v_cmp_eq_u32_e32 vcc, v1, v2
	s_and_saveexec_b64 s[12:13], vcc
	s_cbranch_execz .LBB0_82
	s_add_u32 s10, s84, 0xc10200
	s_addc_u32 s11, s85, 0
	s_mov_b32 s3, 1
	s_branch .LBB0_75

;     __device__ __forceinline__ void operator()(const f32x4 (&acc)[2][2][4][2], const Unit& u, int wr, int wc, int fr, int fq) const {
;         const int row0 = wr * 64 + fr, col0 = u.pn * BM + wc * 32 + 4 * fq, kind = u.pn >> 3;
;         const float* gm = kind == 2 ? g2 : kind == 4 ? g4 : kind == 5 ? g5 : g1;
;         const float one = (kind == 1 || kind == 4) ? 1.0f : 0.0f, gs = (kind == 0 || kind == 3) ? 0.0f : 1.0f;
; #pragma unroll
;         for (int bj = 0; bj < 2; ++bj)
; #pragma unroll
;             for (int n = 0; n < 2; ++n) { const int col = col0 + bj * HALF + n * 16;
;                 const f32x4 bv = *(const f32x4*)(bias + col) + one, gv = *(const f32x4*)(gm + (col & (DM - 1))) * gs + (1.0f - gs);
; #pragma unroll
;                 for (int ai = 0; ai < 2; ++ai)
; #pragma unroll
;                     for (int m = 0; m < 4; ++m) *(f32x4*)(C + (size_t)(row0 + ai * HALF + m * 16) * NADA + col) = (acc[ai][bj][m][n] + bv) * gv; }
.LBB0_129:
	s_lshl_b32 s0, s64, 8
	v_or_b32_e32 v152, s0, v173
	v_ashrrev_i32_e32 v153, 31, v152
	v_readlane_b32 s68, v254, 17
	v_lshlrev_b64 v[168:169], 2, v[152:153]
	v_readlane_b32 s70, v254, 19
	v_readlane_b32 s71, v254, 20
	v_bitop3_b32 v153, s0, v180, v173 bitop3:0xc8
	v_lshlrev_b32_e32 v153, 2, v153
	v_lshl_add_u64 v[176:177], s[70:71], 0, v[168:169]
	global_load_dwordx4 v[190:193], v[176:177], off
	global_load_dwordx4 v[186:189], v153, s[16:17]
	s_cmp_eq_u32 s9, 1
	s_movk_i32 s18, 0x77c
	s_cselect_b64 s[0:1], -1, 0
	s_cmp_eq_u32 s9, 4
	v_bitop3_b32 v153, v152, s18, 16 bitop3:0xc8
	s_cselect_b64 s[18:19], -1, 0
	s_or_b64 s[0:1], s[0:1], s[18:19]
	s_cmp_lt_u32 s64, 8
	v_cndmask_b32_e64 v170, 0, 1.0, s[0:1]
	s_cselect_b64 s[0:1], -1, 0
	s_cmp_eq_u32 s9, 3
	s_cselect_b64 s[18:19], -1, 0
	s_or_b64 s[0:1], s[0:1], s[18:19]
	v_cndmask_b32_e64 v172, 1.0, 0, s[0:1]
	v_sub_f32_e32 v174, 1.0, v172
	v_lshl_add_u64 v[154:155], v[132:133], 0, v[168:169]
	v_lshl_add_u64 v[156:157], v[134:135], 0, v[168:169]
	v_lshl_add_u64 v[158:159], v[136:137], 0, v[168:169]
	v_lshl_add_u64 v[160:161], v[138:139], 0, v[168:169]
	v_lshl_add_u64 v[162:163], v[140:141], 0, v[168:169]
	v_lshl_add_u64 v[164:165], v[142:143], 0, v[168:169]
	v_lshl_add_u64 v[166:167], v[144:145], 0, v[168:169]
	v_lshl_add_u64 v[168:169], v[146:147], 0, v[168:169]
	s_movk_i32 s0, 0x7ec
	s_mov_b64 s[18:19], s[12:13]
	s_mov_b32 s64, s8
	s_and_b64 vcc, exec, s[14:15]
	v_readlane_b32 s69, v254, 18
	v_readlane_b32 s72, v254, 21
	v_readlane_b32 s73, v254, 22
	v_readlane_b32 s74, v254, 23
	v_readlane_b32 s75, v254, 24
	v_readlane_b32 s76, v254, 25
	v_readlane_b32 s77, v254, 26
	v_readlane_b32 s78, v254, 27
	v_readlane_b32 s79, v254, 28
	v_readlane_b32 s80, v254, 29
	v_readlane_b32 s81, v254, 30
	v_readlane_b32 s82, v254, 31
	v_readlane_b32 s83, v254, 32
	s_waitcnt vmcnt(0)
	v_pk_add_f32 v[190:191], v[170:171], v[190:191] op_sel_hi:[0,1]
	v_pk_add_f32 v[192:193], v[170:171], v[192:193] op_sel_hi:[0,1]
	v_pk_fma_f32 v[188:189], v[172:173], v[188:189], v[174:175] op_sel_hi:[0,1,0]
	v_pk_fma_f32 v[186:187], v[172:173], v[186:187], v[174:175] op_sel_hi:[0,1,0]
	v_pk_add_f32 v[126:127], v[126:127], v[192:193]
	v_pk_add_f32 v[124:125], v[124:125], v[190:191]
	v_pk_add_f32 v[122:123], v[122:123], v[192:193]
	v_pk_add_f32 v[120:121], v[120:121], v[190:191]
	v_pk_add_f32 v[118:119], v[118:119], v[192:193]
	v_pk_add_f32 v[116:117], v[116:117], v[190:191]
	v_pk_add_f32 v[114:115], v[114:115], v[192:193]
	v_pk_add_f32 v[112:113], v[112:113], v[190:191]
	v_pk_add_f32 v[194:195], v[110:111], v[192:193]
	v_pk_add_f32 v[196:197], v[108:109], v[190:191]
	v_pk_add_f32 v[198:199], v[106:107], v[192:193]
	v_pk_add_f32 v[200:201], v[104:105], v[190:191]
	v_pk_add_f32 v[202:203], v[102:103], v[192:193]
	v_pk_add_f32 v[204:205], v[100:101], v[190:191]
	v_pk_add_f32 v[192:193], v[98:99], v[192:193]
	v_pk_add_f32 v[190:191], v[96:97], v[190:191]
	v_pk_mul_f32 v[96:97], v[124:125], v[186:187]
	v_pk_mul_f32 v[98:99], v[126:127], v[188:189]
	v_pk_mul_f32 v[100:101], v[120:121], v[186:187]
	v_pk_mul_f32 v[102:103], v[122:123], v[188:189]
	v_pk_mul_f32 v[104:105], v[116:117], v[186:187]
	v_pk_mul_f32 v[106:107], v[118:119], v[188:189]
	v_pk_mul_f32 v[108:109], v[112:113], v[186:187]
	v_pk_mul_f32 v[110:111], v[114:115], v[188:189]
	v_pk_mul_f32 v[112:113], v[196:197], v[186:187]
	v_pk_mul_f32 v[114:115], v[194:195], v[188:189]
	v_pk_mul_f32 v[116:117], v[200:201], v[186:187]
	v_pk_mul_f32 v[118:119], v[198:199], v[188:189]
	v_pk_mul_f32 v[120:121], v[204:205], v[186:187]
	v_pk_mul_f32 v[122:123], v[202:203], v[188:189]
	v_pk_mul_f32 v[124:125], v[190:191], v[186:187]
	v_pk_mul_f32 v[126:127], v[192:193], v[188:189]
	global_store_dwordx4 v[154:155], v[96:99], off sc1
	global_store_dwordx4 v[156:157], v[100:103], off sc1
	global_store_dwordx4 v[158:159], v[104:107], off sc1
	global_store_dwordx4 v[160:161], v[108:111], off sc1
	global_store_dwordx4 v[162:163], v[112:115], off sc1
	global_store_dwordx4 v[164:165], v[116:119], off sc1
	global_store_dwordx4 v[166:167], v[120:123], off sc1
	global_store_dwordx4 v[168:169], v[124:127], off sc1
	global_load_dwordx4 v[96:99], v[176:177], off offset:64
	v_lshlrev_b32_e32 v100, 2, v153
	global_load_dwordx4 v[100:103], v100, s[16:17]
	v_bitop3_b32 v116, v152, s0, v181 bitop3:0xc8
	s_movk_i32 s0, 0x7fc
	s_waitcnt vmcnt(0)
	v_pk_add_f32 v[96:97], v[170:171], v[96:97] op_sel_hi:[0,1]
	v_pk_add_f32 v[98:99], v[170:171], v[98:99] op_sel_hi:[0,1]
	v_pk_fma_f32 v[102:103], v[172:173], v[102:103], v[174:175] op_sel_hi:[0,1,0]
	v_pk_fma_f32 v[100:101], v[172:173], v[100:101], v[174:175] op_sel_hi:[0,1,0]
	v_pk_add_f32 v[94:95], v[94:95], v[98:99]
	v_pk_add_f32 v[92:93], v[92:93], v[96:97]
	v_pk_add_f32 v[90:91], v[90:91], v[98:99]
	v_pk_add_f32 v[88:89], v[88:89], v[96:97]
	v_pk_add_f32 v[86:87], v[86:87], v[98:99]
	v_pk_add_f32 v[84:85], v[84:85], v[96:97]
	v_pk_add_f32 v[82:83], v[82:83], v[98:99]
	v_pk_add_f32 v[80:81], v[80:81], v[96:97]
	v_pk_add_f32 v[104:105], v[78:79], v[98:99]
	v_pk_add_f32 v[106:107], v[76:77], v[96:97]
	v_pk_add_f32 v[108:109], v[74:75], v[98:99]
	v_pk_add_f32 v[110:111], v[72:73], v[96:97]
	v_pk_add_f32 v[112:113], v[70:71], v[98:99]
	v_pk_add_f32 v[114:115], v[68:69], v[96:97]
	v_pk_add_f32 v[98:99], v[66:67], v[98:99]
	v_pk_add_f32 v[96:97], v[64:65], v[96:97]
	v_pk_mul_f32 v[64:65], v[92:93], v[100:101]
	v_pk_mul_f32 v[66:67], v[94:95], v[102:103]
	v_pk_mul_f32 v[68:69], v[88:89], v[100:101]
	v_pk_mul_f32 v[70:71], v[90:91], v[102:103]
	v_pk_mul_f32 v[72:73], v[84:85], v[100:101]
	v_pk_mul_f32 v[74:75], v[86:87], v[102:103]
	v_pk_mul_f32 v[76:77], v[80:81], v[100:101]
	v_pk_mul_f32 v[78:79], v[82:83], v[102:103]
	v_pk_mul_f32 v[80:81], v[106:107], v[100:101]
	v_pk_mul_f32 v[82:83], v[104:105], v[102:103]
	v_pk_mul_f32 v[84:85], v[110:111], v[100:101]
	v_pk_mul_f32 v[86:87], v[108:109], v[102:103]
	v_pk_mul_f32 v[88:89], v[114:115], v[100:101]
	v_pk_mul_f32 v[90:91], v[112:113], v[102:103]
	v_pk_mul_f32 v[92:93], v[96:97], v[100:101]
	v_pk_mul_f32 v[94:95], v[98:99], v[102:103]
	global_store_dwordx4 v[154:155], v[64:67], off offset:64 sc1
	global_store_dwordx4 v[156:157], v[68:71], off offset:64 sc1
	global_store_dwordx4 v[158:159], v[72:75], off offset:64 sc1
	global_store_dwordx4 v[160:161], v[76:79], off offset:64 sc1
	global_store_dwordx4 v[162:163], v[80:83], off offset:64 sc1
	global_store_dwordx4 v[164:165], v[84:87], off offset:64 sc1
	global_store_dwordx4 v[166:167], v[88:91], off offset:64 sc1
	global_store_dwordx4 v[168:169], v[92:95], off offset:64 sc1
	global_load_dwordx4 v[64:67], v[176:177], off offset:512
	v_lshlrev_b32_e32 v68, 2, v116
	global_load_dwordx4 v[68:71], v68, s[16:17]
	v_bitop3_b32 v84, v152, s0, v182 bitop3:0xc8
	s_waitcnt vmcnt(0)
;     __device__ __forceinline__ void operator()(const f32x4 (&acc)[2][2][4][2], const Unit& u, int wr, int wc, int fr, int fq) const {
;     ...
;         for (int bj = 0; bj < 2; ++bj)
; #pragma unroll
;             for (int n = 0; n < 2; ++n) { const int col = col0 + bj * HALF + n * 16;
;                 const f32x4 bv = *(const f32x4*)(bias + col) + one, gv = *(const f32x4*)(gm + (col & (DM - 1))) * gs + (1.0f - gs);
; #pragma unroll
;                 for (int ai = 0; ai < 2; ++ai)
; #pragma unroll
;                     for (int m = 0; m < 4; ++m) *(f32x4*)(C + (size_t)(row0 + ai * HALF + m * 16) * NADA + col) = (acc[ai][bj][m][n] + bv) * gv; }
	v_pk_add_f32 v[64:65], v[170:171], v[64:65] op_sel_hi:[0,1]
	v_pk_add_f32 v[66:67], v[170:171], v[66:67] op_sel_hi:[0,1]
	v_pk_fma_f32 v[70:71], v[172:173], v[70:71], v[174:175] op_sel_hi:[0,1,0]
	v_pk_fma_f32 v[68:69], v[172:173], v[68:69], v[174:175] op_sel_hi:[0,1,0]
	v_pk_add_f32 v[62:63], v[62:63], v[66:67]
	v_pk_add_f32 v[60:61], v[60:61], v[64:65]
	v_pk_add_f32 v[58:59], v[58:59], v[66:67]
	v_pk_add_f32 v[56:57], v[56:57], v[64:65]
	v_pk_add_f32 v[54:55], v[54:55], v[66:67]
	v_pk_add_f32 v[52:53], v[52:53], v[64:65]
	v_pk_add_f32 v[50:51], v[50:51], v[66:67]
	v_pk_add_f32 v[48:49], v[48:49], v[64:65]
	v_pk_add_f32 v[72:73], v[46:47], v[66:67]
	v_pk_add_f32 v[74:75], v[44:45], v[64:65]
	v_pk_add_f32 v[76:77], v[42:43], v[66:67]
	v_pk_add_f32 v[78:79], v[40:41], v[64:65]
	v_pk_add_f32 v[80:81], v[38:39], v[66:67]
	v_pk_add_f32 v[82:83], v[36:37], v[64:65]
	v_pk_add_f32 v[66:67], v[34:35], v[66:67]
	v_pk_add_f32 v[64:65], v[32:33], v[64:65]
	v_pk_mul_f32 v[32:33], v[60:61], v[68:69]
	v_pk_mul_f32 v[34:35], v[62:63], v[70:71]
	v_pk_mul_f32 v[36:37], v[56:57], v[68:69]
	v_pk_mul_f32 v[38:39], v[58:59], v[70:71]
	v_pk_mul_f32 v[40:41], v[52:53], v[68:69]
	v_pk_mul_f32 v[42:43], v[54:55], v[70:71]
	v_pk_mul_f32 v[44:45], v[48:49], v[68:69]
	v_pk_mul_f32 v[46:47], v[50:51], v[70:71]
	v_pk_mul_f32 v[48:49], v[74:75], v[68:69]
	v_pk_mul_f32 v[50:51], v[72:73], v[70:71]
	v_pk_mul_f32 v[52:53], v[78:79], v[68:69]
	v_pk_mul_f32 v[54:55], v[76:77], v[70:71]
	v_pk_mul_f32 v[56:57], v[82:83], v[68:69]
	v_pk_mul_f32 v[58:59], v[80:81], v[70:71]
	v_pk_mul_f32 v[60:61], v[64:65], v[68:69]
	v_pk_mul_f32 v[62:63], v[66:67], v[70:71]
	global_store_dwordx4 v[154:155], v[32:35], off offset:512 sc1
	global_store_dwordx4 v[156:157], v[36:39], off offset:512 sc1
	global_store_dwordx4 v[158:159], v[40:43], off offset:512 sc1
	global_store_dwordx4 v[160:161], v[44:47], off offset:512 sc1
	global_store_dwordx4 v[162:163], v[48:51], off offset:512 sc1
	global_store_dwordx4 v[164:165], v[52:55], off offset:512 sc1
	global_store_dwordx4 v[166:167], v[56:59], off offset:512 sc1
	global_store_dwordx4 v[168:169], v[60:63], off offset:512 sc1
	global_load_dwordx4 v[32:35], v[176:177], off offset:576
	v_lshlrev_b32_e32 v36, 2, v84
	global_load_dwordx4 v[36:39], v36, s[16:17]
	s_mov_b64 s[16:17], s[10:11]
	s_waitcnt vmcnt(0)
	v_pk_add_f32 v[32:33], v[170:171], v[32:33] op_sel_hi:[0,1]
	v_pk_add_f32 v[34:35], v[170:171], v[34:35] op_sel_hi:[0,1]
	v_pk_fma_f32 v[38:39], v[172:173], v[38:39], v[174:175] op_sel_hi:[0,1,0]
	v_pk_fma_f32 v[36:37], v[172:173], v[36:37], v[174:175] op_sel_hi:[0,1,0]
	v_pk_add_f32 v[30:31], v[30:31], v[34:35]
	v_pk_add_f32 v[28:29], v[28:29], v[32:33]
	v_pk_add_f32 v[26:27], v[26:27], v[34:35]
	v_pk_add_f32 v[24:25], v[24:25], v[32:33]
	v_pk_add_f32 v[22:23], v[22:23], v[34:35]
	v_pk_add_f32 v[20:21], v[20:21], v[32:33]
	v_pk_add_f32 v[18:19], v[18:19], v[34:35]
	v_pk_add_f32 v[16:17], v[16:17], v[32:33]
	v_pk_add_f32 v[40:41], v[14:15], v[34:35]
	v_pk_add_f32 v[42:43], v[12:13], v[32:33]
	v_pk_add_f32 v[44:45], v[10:11], v[34:35]
	v_pk_add_f32 v[46:47], v[8:9], v[32:33]
	v_pk_add_f32 v[48:49], v[6:7], v[34:35]
	v_pk_add_f32 v[50:51], v[4:5], v[32:33]
	v_pk_add_f32 v[34:35], v[2:3], v[34:35]
	v_pk_add_f32 v[32:33], v[0:1], v[32:33]
	v_pk_mul_f32 v[0:1], v[28:29], v[36:37]
	v_pk_mul_f32 v[2:3], v[30:31], v[38:39]
	v_pk_mul_f32 v[4:5], v[24:25], v[36:37]
	v_pk_mul_f32 v[6:7], v[26:27], v[38:39]
	v_pk_mul_f32 v[8:9], v[20:21], v[36:37]
	v_pk_mul_f32 v[10:11], v[22:23], v[38:39]
	v_pk_mul_f32 v[12:13], v[16:17], v[36:37]
	v_pk_mul_f32 v[14:15], v[18:19], v[38:39]
	v_pk_mul_f32 v[16:17], v[42:43], v[36:37]
	v_pk_mul_f32 v[18:19], v[40:41], v[38:39]
	v_pk_mul_f32 v[20:21], v[46:47], v[36:37]
	v_pk_mul_f32 v[22:23], v[44:45], v[38:39]
	v_pk_mul_f32 v[24:25], v[50:51], v[36:37]
	v_pk_mul_f32 v[26:27], v[48:49], v[38:39]
	v_pk_mul_f32 v[28:29], v[32:33], v[36:37]
	v_pk_mul_f32 v[30:31], v[34:35], v[38:39]
	global_store_dwordx4 v[154:155], v[0:3], off offset:576 sc1
	global_store_dwordx4 v[156:157], v[4:7], off offset:576 sc1
	global_store_dwordx4 v[158:159], v[8:11], off offset:576 sc1
	global_store_dwordx4 v[160:161], v[12:15], off offset:576 sc1
	global_store_dwordx4 v[162:163], v[16:19], off offset:576 sc1
	global_store_dwordx4 v[164:165], v[20:23], off offset:576 sc1
	global_store_dwordx4 v[166:167], v[24:27], off offset:576 sc1
	global_store_dwordx4 v[168:169], v[28:31], off offset:576 sc1
	s_cbranch_vccnz .LBB0_143

; __global__ void __launch_bounds__(NTHREADS, 2) fwd_megakernel(Params p) {
;     ...
;         gemm_phase(lds, DM, DM, S, E);
;         if (threadIdx.x == 0) { __builtin_amdgcn_fence(__ATOMIC_RELEASE, "agent"); asm volatile("s_waitcnt vmcnt(0)" ::: "memory");
;             __hip_atomic_fetch_add((unsigned*)(ws + WS_BAR) + ADA_FLAG, 1u, __ATOMIC_RELAXED, __HIP_MEMORY_SCOPE_AGENT); }
.LBB0_145:
	s_barrier
	s_mov_b64 s[0:1], exec
	v_readlane_b32 s6, v255, 4
	v_readlane_b32 s7, v255, 5
	s_and_b64 s[6:7], s[0:1], s[6:7]
	s_mov_b64 exec, s[6:7]
	s_cbranch_execz .LBB0_149
	s_mov_b64 s[6:7], exec
	s_nop 0
	s_waitcnt vmcnt(0) lgkmcnt(0)
	s_waitcnt vmcnt(0)
	v_mbcnt_lo_u32_b32 v0, s6, 0
	v_mbcnt_hi_u32_b32 v0, s7, v0
	v_cmp_eq_u32_e32 vcc, 0, v0
	s_and_saveexec_b64 s[8:9], vcc
	s_cbranch_execz .LBB0_148
	s_bcnt1_i32_b64 s3, s[6:7]
	v_mov_b32_e32 v0, 0xc15000
	v_mov_b32_e32 v1, s3
	global_atomic_add v0, v1, s[84:85] offset:1536
